# lever 2: GEMM phase prologues issue K-tile 1's six LDS-DMA stages before the first wait (one counted vmcnt(8) + barrier, then vmcnt(6) + barrier) in all four GEMM instances
# baseline (speedup 1.0000x reference)
; #define PG8_STAGE(bufoff, gbase, voff) do { _Pragma("unroll") for (int _i = 0; _i < 2; ++_i) \
;         __builtin_amdgcn_global_load_lds((const unsigned*)((const char*)(gbase) + (voff)[_i]), (LAS unsigned*)(lds + (bufoff) + ldsw + _i * 8192), 16, 0, 0); } while (0)
; #define PG8_WAIT_V(n) asm volatile("s_waitcnt vmcnt(" #n ")" ::: "memory")
; #define PG8_BAR __builtin_amdgcn_s_barrier()
; template <class Epi, class Sched>
; __device__ __forceinline__ void gemm_phase(LAS unsigned char* lds, const Gemm g, const Sched& S, const Epi& E, const int tid) {
;     const int wid = __builtin_amdgcn_readfirstlane(tid >> 6), lane = tid & 63, wr = wid >> 2, wc = wid & 3, fr = lane & 15, fq = lane >> 4;
;     const int K = g.K, nt = K / BK;
;     unsigned voffA[2], voffB[2];
; #pragma unroll
;     for (int i = 0; i < 2; ++i) { int R, C; stage_rc(tid * 16 + i * 8192, R, C); const int Rb = Epi::PERM ? ((R & ~31) + perm32(R & 31)) : R;
;         voffA[i] = (unsigned)(R * K + C) * 2u; voffB[i] = (unsigned)(Rb * K + C) * 2u; }
;     const size_t kstep = (size_t)(BK * 2);
;     const size_t hstep = (size_t)HALF * K * 2;
;     const size_t tstep = 2 * hstep;
;     const unsigned ldsw = (unsigned)wid * 1024u;
;     const int aoff = lds_byte(wr * 64 + fr, fq * 8), boff = lds_byte(wc * 32 + fr, fq * 8);
;     ...
;     const char* cA = (const char*)g.A + (size_t)cur.pm * tstep; const char* cB = (const char*)g.Bt + (size_t)cur.pn * tstep;
;     PG8_STAGE(PG8_SB(0, 0), cB, voffB); PG8_STAGE(PG8_SB(0, 1), cB + hstep, voffB); PG8_STAGE(PG8_SA(0, 0), cA, voffA); PG8_STAGE(PG8_SA(0, 1), cA + hstep, voffA);
;     if (wr == 1) PG8_BAR;
;     PG8_WAIT_V(2); PG8_BAR;
;     PG8_STAGE(PG8_SB(1, 0), cB + kstep, voffB); PG8_STAGE(PG8_SA(1, 0), cA + kstep, voffA); PG8_STAGE(PG8_SB(1, 1), cB + hstep + kstep, voffB);
;     PG8_WAIT_V(6); PG8_BAR;
.LBB0_160:
	s_and_b64 s[4:5], s[4:5], exec
	s_cselect_b32 s4, 0x8000, 0
	v_readlane_b32 s3, v254, 54
	s_add_u32 s91, s3, s4
	v_readlane_b32 s3, v254, 56
	s_addc_u32 s92, s3, 0
	v_readlane_b32 s64, v252, 63
	s_add_u32 s4, s66, 0x40080
	v_mov_b32_e32 v139, v193
	v_readlane_b32 s65, v253, 0
	v_lshl_add_u64 v[0:1], v[0:1], 0, s[68:69]
	s_addc_u32 s5, s67, 0
	s_add_i32 m0, s75, 0x18000
	v_mov_b32_e32 v137, v193
	v_lshl_add_u64 v[10:11], s[64:65], 0, v[138:139]
	v_lshl_add_u64 v[2:3], v[2:3], 0, s[68:69]
	global_load_lds_dwordx4 v[0:1], off
	s_add_i32 m0, s75, 0x1a000
	s_add_i32 s93, s75, 0x8000
	v_lshl_add_u64 v[12:13], s[64:65], 0, v[136:137]
	v_and_b32_e32 v18, 15, v132
	v_lshrrev_b32_e32 v14, 1, v132
	v_lshl_add_u64 v[10:11], v[10:11], 0, s[68:69]
	global_load_lds_dwordx4 v[2:3], off
	s_mov_b32 m0, s93
	s_add_i32 s94, s75, 0xa000
	v_and_b32_e32 v19, 24, v14
	v_lshlrev_b32_e32 v14, 6, v18
	v_lshl_add_u64 v[12:13], v[12:13], 0, s[68:69]
	global_load_lds_dwordx4 v[10:11], off
	s_mov_b32 m0, s94
	s_nop 0
	v_lshl_or_b32 v20, v19, 1, v14
	v_lshl_add_u64 v[14:15], s[4:5], 0, v[192:193]
	global_load_lds_dwordx4 v[12:13], off
	s_add_i32 m0, s75, 0x1c000
	v_lshl_add_u64 v[16:17], s[4:5], 0, v[134:135]
	global_load_lds_dwordx4 v[14:15], off
	s_add_i32 m0, s75, 0x1e000
	v_lshlrev_b32_e32 v0, 14, v8
	global_load_lds_dwordx4 v[16:17], off
	s_lshl_b32 s22, s22, 5
	v_and_b32_e32 v0, 0xffff8000, v0
	v_lshlrev_b32_e32 v21, 2, v18
	s_and_b32 s22, s22, 0x60
	v_lshl_add_u32 v0, v7, 11, v0
	v_and_b32_e32 v1, 1, v8
	v_and_b32_e32 v22, 32, v21
	s_lshl_b32 s23, s22, 2
	s_lshl_b32 s38, s7, 8
	s_waitcnt lgkmcnt(0)
	v_lshl_or_b32 v165, s7, 6, v18
	s_lshl_b32 s7, s7, 13
	v_lshl_or_b32 v0, v1, 6, v0
	s_movk_i32 s3, 0x100
	s_add_i32 s23, s23, 0
	s_add_i32 s39, s38, 0
	v_bitop3_b32 v18, v20, s7, v22 bitop3:0xde
	s_lshl_b32 s7, s22, 7
	v_lshl_add_u32 v140, v9, 1, v0
	v_lshlrev_b32_e32 v0, 14, v4
	v_cmp_gt_i32_e64 s[4:5], s3, v132
	v_readlane_b32 s3, v254, 40
	s_cmpk_lt_u32 s6, 0x100
	v_and_b32_e32 v0, 0xffff8000, v0
	s_waitcnt vmcnt(8)
	s_barrier
	s_waitcnt vmcnt(6)
	s_cselect_b64 s[50:51], -1, 0
	s_add_i32 s6, s3, s38
	v_lshl_add_u32 v0, v5, 11, v0
	v_and_b32_e32 v1, 1, v4
	v_bitop3_b32 v166, s7, v20, v22 bitop3:0xf6
	s_add_i32 s23, s23, 0x20400
	v_add_u32_e32 v168, s6, v21
	s_add_i32 s39, s39, 0x20200
	v_lshl_or_b32 v0, v1, 6, v0
	v_readlane_b32 s6, v252, 59
	s_mov_b32 s90, 0
	v_lshl_add_u32 v164, v132, 2, s3
	v_lshl_add_u32 v167, v19, 2, s23
	v_add_u32_e32 v169, s39, v21
	v_or_b32_e32 v170, s22, v19
	v_mov_b32_e32 v141, v193
	v_lshl_add_u32 v142, v6, 1, v0
	v_mov_b32_e32 v143, v193
	v_add_u32_e32 v171, 0, v18
	s_mov_b32 s52, s6
	v_readlane_b32 s53, v252, 58
	s_barrier
	v_readlane_b32 s7, v252, 60
	s_branch .LBB0_163

; #define PG8_STAGE(bufoff, gbase, voff) do { _Pragma("unroll") for (int _i = 0; _i < 2; ++_i) \
;         __builtin_amdgcn_global_load_lds((const unsigned*)((const char*)(gbase) + (voff)[_i]), (LAS unsigned*)(lds + (bufoff) + ldsw + _i * 8192), 16, 0, 0); } while (0)
; #define PG8_WAIT_V(n) asm volatile("s_waitcnt vmcnt(" #n ")" ::: "memory")
; #define PG8_BAR __builtin_amdgcn_s_barrier()
; template <class Epi, class Sched>
; __device__ __forceinline__ void gemm_phase(LAS unsigned char* lds, const Gemm g, const Sched& S, const Epi& E, const int tid) {
;     const int wid = __builtin_amdgcn_readfirstlane(tid >> 6), lane = tid & 63, wr = wid >> 2, wc = wid & 3, fr = lane & 15, fq = lane >> 4;
;     const int K = g.K, nt = K / BK;
;     unsigned voffA[2], voffB[2];
; #pragma unroll
;     for (int i = 0; i < 2; ++i) { int R, C; stage_rc(tid * 16 + i * 8192, R, C); const int Rb = Epi::PERM ? ((R & ~31) + perm32(R & 31)) : R;
;         voffA[i] = (unsigned)(R * K + C) * 2u; voffB[i] = (unsigned)(Rb * K + C) * 2u; }
;     const size_t kstep = (size_t)(BK * 2);
;     const size_t hstep = (size_t)HALF * K * 2;
;     const size_t tstep = 2 * hstep;
;     const unsigned ldsw = (unsigned)wid * 1024u;
;     const int aoff = lds_byte(wr * 64 + fr, fq * 8), boff = lds_byte(wc * 32 + fr, fq * 8);
;     ...
;     const char* cA = (const char*)g.A + (size_t)cur.pm * tstep; const char* cB = (const char*)g.Bt + (size_t)cur.pn * tstep;
;     PG8_STAGE(PG8_SB(0, 0), cB, voffB); PG8_STAGE(PG8_SB(0, 1), cB + hstep, voffB); PG8_STAGE(PG8_SA(0, 0), cA, voffA); PG8_STAGE(PG8_SA(0, 1), cA + hstep, voffA);
;     if (wr == 1) PG8_BAR;
;     PG8_WAIT_V(2); PG8_BAR;
;     PG8_STAGE(PG8_SB(1, 0), cB + kstep, voffB); PG8_STAGE(PG8_SA(1, 0), cA + kstep, voffA); PG8_STAGE(PG8_SB(1, 1), cB + hstep + kstep, voffB);
;     PG8_WAIT_V(6); PG8_BAR;
.LBB0_254:
	v_readlane_b32 s64, v255, 5
	v_mov_b32_e32 v165, v193
	v_readlane_b32 s65, v255, 6
	v_mov_b32_e32 v169, v193
	v_readlane_b32 s38, v254, 22
	v_lshl_add_u64 v[0:1], s[64:65], 0, v[164:165]
	v_lshl_add_u64 v[2:3], s[64:65], 0, v[168:169]
	v_mov_b32_e32 v163, v193
	v_readlane_b32 s39, v254, 23
	s_add_i32 m0, s73, 0x18000
	v_lshl_add_u64 v[0:1], v[0:1], 0, s[68:69]
	v_lshl_add_u64 v[4:5], s[38:39], 0, v[162:163]
	v_mov_b32_e32 v167, v193
	global_load_lds_dwordx4 v[0:1], off
	v_lshl_add_u64 v[0:1], v[2:3], 0, s[68:69]
	s_add_i32 m0, s73, 0x1a000
	s_add_i32 s82, s73, 0x8000
	v_lshl_add_u64 v[6:7], s[38:39], 0, v[166:167]
	global_load_lds_dwordx4 v[0:1], off
	v_lshl_add_u64 v[0:1], v[4:5], 0, s[68:69]
	s_mov_b32 m0, s82
	s_add_i32 s83, s73, 0xa000
	v_readlane_b32 s8, v255, 7
	global_load_lds_dwordx4 v[0:1], off
	v_lshl_add_u64 v[0:1], v[6:7], 0, s[68:69]
	s_mov_b32 m0, s83
	v_readlane_b32 s9, v255, 8
	global_load_lds_dwordx4 v[0:1], off
	s_add_i32 m0, s73, 0x1c000
	v_lshl_add_u64 v[0:1], s[8:9], 0, v[164:165]
	global_load_lds_dwordx4 v[0:1], off
	v_lshl_add_u64 v[0:1], s[8:9], 0, v[168:169]
	s_add_i32 m0, s73, 0x1e000
	v_lshlrev_b32_e32 v3, 2, v214
	global_load_lds_dwordx4 v[0:1], off
	v_bfe_u32 v0, v160, 4, 2
	v_lshlrev_b32_e32 v1, 4, v0
	s_and_b32 s5, s5, 3
	v_lshl_or_b32 v2, v214, 6, v1
	s_lshl_b32 s7, s6, 13
	v_and_b32_e32 v4, 32, v3
	s_lshl_b32 s3, s6, 6
	v_bitop3_b32 v2, v2, s7, v4 bitop3:0xde
	v_or_b32_e32 v1, v1, v170
	s_lshl_b32 s7, s5, 12
	v_bitop3_b32 v216, v1, s7, v215 bitop3:0xde
	s_movk_i32 s7, 0x100
	s_cmpk_lt_u32 s4, 0x100
	v_cmp_gt_i32_e64 s[8:9], s7, v160
	s_cselect_b64 s[50:51], -1, 0
	v_readlane_b32 s7, v254, 40
	s_lshl_b32 s6, s6, 8
	v_xor_b32_e32 v1, 16, v228
	v_lshl_add_u32 v217, v160, 2, s7
	s_add_i32 s7, s7, s6
	s_add_i32 s6, s6, 0
	s_add_i32 s6, s6, 0x20200
	v_add_u32_e32 v218, s7, v3
	v_add_u32_e32 v219, s6, v3
	v_and_b32_e32 v3, 64, v228
	v_add_u32_e32 v3, 64, v3
	v_cmp_lt_i32_e32 vcc, v1, v3
	v_and_b32_e32 v4, 1, v171
	s_lshl_b32 s4, s5, 7
	v_cndmask_b32_e32 v1, v228, v1, vcc
	v_lshlrev_b32_e32 v220, 2, v1
	v_xor_b32_e32 v1, 32, v228
	v_cmp_lt_i32_e32 vcc, v1, v3
	v_lshlrev_b32_e32 v3, 14, v171
	v_and_b32_e32 v3, 0xffff8000, v3
	v_lshl_add_u32 v3, v173, 11, v3
	v_lshl_or_b32 v3, v4, 6, v3
	v_lshl_add_u32 v174, v210, 1, v3
	v_lshlrev_b32_e32 v3, 14, v211
	s_add_i32 s4, s4, 0
	v_and_b32_e32 v3, 0xffff8000, v3
	v_lshlrev_b32_e32 v172, 3, v0
	s_waitcnt vmcnt(8)
	s_barrier
	s_waitcnt vmcnt(6)
	v_lshlrev_b32_e32 v0, 5, v0
	s_add_i32 s4, s4, 0x20400
	v_cndmask_b32_e32 v1, v228, v1, vcc
	v_lshl_add_u32 v3, v212, 11, v3
	v_and_b32_e32 v4, 1, v211
	s_or_b32 s15, s5, -8
	v_lshlrev_b32_e32 v221, 2, v1
	v_lshl_or_b32 v1, s5, 5, v172
	v_lshl_or_b32 v229, s5, 6, v172
	v_lshl_or_b32 v3, v4, 6, v3
	v_add_u32_e32 v231, s4, v0
	v_readlane_b32 s4, v254, 18
	v_mov_b32_e32 v175, v193
	v_lshl_add_u32 v176, v213, 1, v3
	v_mov_b32_e32 v177, v193
	s_mov_b32 s78, 0
	v_add_u32_e32 v230, 0, v2
	v_lshlrev_b32_e32 v232, 1, v1
	s_mov_b32 s53, s4
	v_readlane_b32 s52, v254, 15
	s_mov_b64 s[6:7], s[38:39]
	s_barrier
	v_readlane_b32 s5, v254, 19
	s_branch .LBB0_257

; #define PG8_STAGE(bufoff, gbase, voff) do { _Pragma("unroll") for (int _i = 0; _i < 2; ++_i) \
;         __builtin_amdgcn_global_load_lds((const unsigned*)((const char*)(gbase) + (voff)[_i]), (LAS unsigned*)(lds + (bufoff) + ldsw + _i * 8192), 16, 0, 0); } while (0)
; #define PG8_WAIT_V(n) asm volatile("s_waitcnt vmcnt(" #n ")" ::: "memory")
; #define PG8_BAR __builtin_amdgcn_s_barrier()
; template <class Epi, class Sched>
; __device__ __forceinline__ void gemm_phase(LAS unsigned char* lds, const Gemm g, const Sched& S, const Epi& E, const int tid) {
;     const int wid = __builtin_amdgcn_readfirstlane(tid >> 6), lane = tid & 63, wr = wid >> 2, wc = wid & 3, fr = lane & 15, fq = lane >> 4;
;     const int K = g.K, nt = K / BK;
;     unsigned voffA[2], voffB[2];
; #pragma unroll
;     for (int i = 0; i < 2; ++i) { int R, C; stage_rc(tid * 16 + i * 8192, R, C); const int Rb = Epi::PERM ? ((R & ~31) + perm32(R & 31)) : R;
;         voffA[i] = (unsigned)(R * K + C) * 2u; voffB[i] = (unsigned)(Rb * K + C) * 2u; }
;     const size_t kstep = (size_t)(BK * 2);
;     const size_t hstep = (size_t)HALF * K * 2;
;     const size_t tstep = 2 * hstep;
;     const unsigned ldsw = (unsigned)wid * 1024u;
;     const int aoff = lds_byte(wr * 64 + fr, fq * 8), boff = lds_byte(wc * 32 + fr, fq * 8);
;     ...
;     const char* cA = (const char*)g.A + (size_t)cur.pm * tstep; const char* cB = (const char*)g.Bt + (size_t)cur.pn * tstep;
;     PG8_STAGE(PG8_SB(0, 0), cB, voffB); PG8_STAGE(PG8_SB(0, 1), cB + hstep, voffB); PG8_STAGE(PG8_SA(0, 0), cA, voffA); PG8_STAGE(PG8_SA(0, 1), cA + hstep, voffA);
;     if (wr == 1) PG8_BAR;
;     PG8_WAIT_V(2); PG8_BAR;
;     PG8_STAGE(PG8_SB(1, 0), cB + kstep, voffB); PG8_STAGE(PG8_SA(1, 0), cA + kstep, voffA); PG8_STAGE(PG8_SB(1, 1), cB + hstep + kstep, voffB);
;     PG8_WAIT_V(6); PG8_BAR;
.LBB0_314:
	v_readlane_b32 s64, v254, 35
	v_mov_b32_e32 v165, v193
	v_readlane_b32 s65, v254, 36
	v_lshrrev_b32_e32 v8, 1, v160
	v_mov_b32_e32 v169, v193
	v_lshl_add_u64 v[0:1], s[64:65], 0, v[164:165]
	v_readlane_b32 s62, v255, 9
	v_and_b32_e32 v8, 24, v8
	v_lshl_add_u64 v[2:3], s[64:65], 0, v[168:169]
	v_mov_b32_e32 v163, v193
	v_readlane_b32 s63, v255, 10
	v_lshlrev_b32_e32 v9, 1, v8
	v_lshlrev_b32_e32 v11, 2, v214
	s_add_i32 m0, s53, 0x18000
	v_lshl_add_u64 v[0:1], v[0:1], 0, s[68:69]
	v_lshl_add_u64 v[4:5], s[62:63], 0, v[162:163]
	v_mov_b32_e32 v167, v193
	v_lshl_or_b32 v10, v214, 6, v9
	s_lshl_b32 s7, s5, 13
	v_and_b32_e32 v12, 32, v11
	global_load_lds_dwordx4 v[0:1], off
	v_lshl_add_u64 v[0:1], v[2:3], 0, s[68:69]
	s_add_i32 m0, s53, 0x1a000
	s_add_i32 s61, s53, 0x8000
	v_lshl_add_u64 v[6:7], s[62:63], 0, v[166:167]
	v_bitop3_b32 v10, v10, s7, v12 bitop3:0xde
	s_lshl_b32 s12, s6, 5
	global_load_lds_dwordx4 v[0:1], off
	v_lshl_add_u64 v[0:1], v[4:5], 0, s[68:69]
	s_mov_b32 m0, s61
	s_add_i32 s70, s53, 0xa000
	v_readlane_b32 s6, v254, 37
	global_load_lds_dwordx4 v[0:1], off
	v_lshl_add_u64 v[0:1], v[6:7], 0, s[68:69]
	s_mov_b32 m0, s70
	v_readlane_b32 s7, v254, 38
	global_load_lds_dwordx4 v[0:1], off
	s_add_i32 m0, s53, 0x1c000
	v_lshl_add_u64 v[0:1], s[6:7], 0, v[164:165]
	global_load_lds_dwordx4 v[0:1], off
	v_lshl_add_u64 v[0:1], s[6:7], 0, v[168:169]
	s_add_i32 m0, s53, 0x1e000
	s_and_b32 s22, s12, 0x60
	global_load_lds_dwordx4 v[0:1], off
	s_lshl_b32 s59, s5, 6
	s_lshl_b32 s60, s22, 7
	v_lshlrev_b32_e32 v1, 14, v171
	s_movk_i32 s3, 0x100
	s_cmpk_lt_u32 s4, 0x100
	v_and_b32_e32 v1, 0xffff8000, v1
	v_cmp_gt_i32_e64 s[6:7], s3, v160
	s_cselect_b64 s[8:9], -1, 0
	v_readlane_b32 s3, v254, 40
	s_lshl_b32 s4, s22, 2
	v_lshl_add_u32 v1, v173, 11, v1
	v_and_b32_e32 v3, 1, v171
	s_add_i32 s4, s3, s4
	v_lshl_or_b32 v1, v3, 6, v1
	v_lshl_add_u32 v156, v8, 2, s4
	s_lshl_b32 s4, s5, 8
	v_lshl_add_u32 v144, v210, 1, v1
	v_lshlrev_b32_e32 v1, 14, v211
	s_add_i32 s5, s4, 0
	v_and_b32_e32 v1, 0xffff8000, v1
	s_waitcnt vmcnt(8)
	s_barrier
	s_waitcnt vmcnt(6)
	v_and_or_b32 v0, s12, 32, v8
	s_add_i32 s12, s5, 0x20400
	s_add_i32 s4, s3, s4
	s_add_i32 s5, s5, 0x20600
	v_lshl_add_u32 v1, v212, 11, v1
	v_and_b32_e32 v3, 1, v211
	v_or_b32_e32 v9, v9, v170
	v_or_b32_e32 v2, 0x800, v170
	v_or_b32_e32 v4, 0xc00, v170
	v_add_u32_e32 v158, s4, v11
	v_add_u32_e32 v159, s5, v11
	v_lshl_or_b32 v1, v3, 6, v1
	v_readlane_b32 s4, v254, 29
	v_bitop3_b32 v154, s60, v9, v215 bitop3:0xf6
	v_lshl_add_u32 v155, v160, 2, s3
	v_add_u32_e32 v157, s12, v11
	v_mov_b32_e32 v145, v193
	v_lshl_add_u32 v146, v213, 1, v1
	v_mov_b32_e32 v147, v193
	s_mov_b32 s71, 0
	v_add_u32_e32 v171, 0, v10
	v_lshlrev_b32_e32 v192, 1, v170
	v_lshlrev_b32_e32 v148, 1, v0
	v_lshlrev_b32_e32 v150, 1, v2
	v_lshlrev_b32_e32 v152, 1, v4
	s_mov_b32 s73, s4
	v_readlane_b32 s12, v254, 28
	s_barrier
	v_readlane_b32 s5, v254, 30
	s_branch .LBB0_317

; #define PG8_STAGE(bufoff, gbase, voff) do { _Pragma("unroll") for (int _i = 0; _i < 2; ++_i) \
;         __builtin_amdgcn_global_load_lds((const unsigned*)((const char*)(gbase) + (voff)[_i]), (LAS unsigned*)(lds + (bufoff) + ldsw + _i * 8192), 16, 0, 0); } while (0)
; #define PG8_WAIT_V(n) asm volatile("s_waitcnt vmcnt(" #n ")" ::: "memory")
; #define PG8_BAR __builtin_amdgcn_s_barrier()
; template <class Epi, class Sched>
; __device__ __forceinline__ void gemm_phase(LAS unsigned char* lds, const Gemm g, const Sched& S, const Epi& E, const int tid) {
;     ...
;     const char* cA = (const char*)g.A + (size_t)cur.pm * tstep; const char* cB = (const char*)g.Bt + (size_t)cur.pn * tstep;
;     PG8_STAGE(PG8_SB(0, 0), cB, voffB); PG8_STAGE(PG8_SB(0, 1), cB + hstep, voffB); PG8_STAGE(PG8_SA(0, 0), cA, voffA); PG8_STAGE(PG8_SA(0, 1), cA + hstep, voffA);
;     if (wr == 1) PG8_BAR;
;     PG8_WAIT_V(2); PG8_BAR;
;     PG8_STAGE(PG8_SB(1, 0), cB + kstep, voffB); PG8_STAGE(PG8_SA(1, 0), cA + kstep, voffA); PG8_STAGE(PG8_SB(1, 1), cB + hstep + kstep, voffB);
;     PG8_WAIT_V(6); PG8_BAR;
; __global__ void __launch_bounds__(512, 2) fwd_kernel(Args a) {
;     ...
;                 const bool has_next = !(l == NL - 1 && s == 2);
;                 const int ln = (s == 2) ? l + 1 : l, sn = (s == 2) ? 0 : s + 1;
;                 const float* gain_n = (sn == 0 ? a.in[4] : sn == 1 ? a.in[8] : a.in[16]) + (size_t)(has_next ? ln : 0) * DM;
;                 const float* scale_n = mod + (size_t)(has_next ? ln : 0) * 8 * NMOD + sn * 3072 + 1024;
;                 bf16_t* xt = has_next ? H : (bf16_t*)nullptr;
;                 const float* gatep = modl + s * 3072 + 2048;
;                 const float coef = (s == 1) ? 1.0f : 0.5f;
;                 const pg8::EpiRes E{XB, XB, a.out, gatep, xt, gain_n, scale_n, STATS, scr, coef};
.LBB0_549:
	s_add_i32 s10, s14, 1
	s_cmp_eq_u32 s14, 2
	s_cselect_b64 s[8:9], -1, 0
	v_readlane_b32 s56, v252, 0
	s_and_b64 s[8:9], s[8:9], exec
	v_readlane_b32 s57, v252, 1
	v_readlane_b32 s58, v252, 2
	v_readlane_b32 s59, v252, 3
	v_readlane_b32 s60, v252, 4
	v_readlane_b32 s61, v252, 5
	v_readlane_b32 s62, v252, 6
	v_readlane_b32 s63, v252, 7
	s_cselect_b32 s3, 0, s10
	s_mov_b64 s[8:9], s[56:57]
	v_readlane_b32 s48, v252, 38
	s_cmp_eq_u32 s3, 1
	v_readlane_b32 s49, v252, 39
	s_cselect_b32 s64, s48, s8
	s_cselect_b32 s65, s49, s9
	s_cmp_eq_u32 s14, 2
	s_cselect_b64 s[8:9], -1, 0
	v_readlane_b32 s50, v252, 40
	v_readlane_b32 s51, v252, 41
	v_readlane_b32 s52, v252, 42
	v_readlane_b32 s53, v252, 43
	v_readlane_b32 s54, v252, 44
	v_readlane_b32 s55, v252, 45
	v_readlane_b32 s56, v252, 46
	v_readlane_b32 s57, v252, 47
	v_readlane_b32 s58, v252, 48
	v_readlane_b32 s59, v252, 49
	v_readlane_b32 s60, v252, 50
	v_readlane_b32 s61, v252, 51
	v_readlane_b32 s62, v252, 52
	v_readlane_b32 s63, v252, 53
	s_and_b64 s[10:11], s[8:9], exec
	v_readlane_b32 s48, v252, 10
	v_readlane_b32 s10, v255, 1
	v_readlane_b32 s50, v252, 12
	v_readlane_b32 s51, v252, 13
	v_readlane_b32 s56, v252, 18
	v_readlane_b32 s57, v252, 19
	v_readlane_b32 s11, v255, 2
	v_readlane_b32 s49, v252, 11
	s_cselect_b32 s51, s57, s65
	s_cselect_b32 s50, s56, s64
	s_and_b64 s[10:11], s[10:11], s[8:9]
	s_xor_b64 s[48:49], s[10:11], -1
	v_readlane_b32 s53, v252, 15
	s_cmp_lg_u64 s[8:9], 0
	v_readlane_b32 s8, v254, 63
	v_readlane_b32 s9, v255, 0
	s_addc_u32 s53, s8, 0
	s_and_b64 s[8:9], s[10:11], exec
	s_cselect_b32 s9, 0, 0
	s_cselect_b32 s8, 0, s53
	s_lshl_b64 s[10:11], s[8:9], 12
	s_add_u32 s50, s50, s10
	s_addc_u32 s51, s51, s11
	s_mul_hi_u32 s9, s8, 0x48000
	s_mul_i32 s8, s8, 0x48000
	s_add_u32 s10, s26, s8
	s_addc_u32 s11, s27, s9
	s_mul_i32 s8, s3, 0xc00
	s_mov_b32 s9, s13
	s_lshl_b64 s[8:9], s[8:9], 2
	s_add_u32 s8, s10, s8
	v_readlane_b32 s54, v252, 16
	s_addc_u32 s9, s11, s9
	v_readlane_b32 s55, v252, 17
	s_add_u32 s54, s8, 0x1000
	s_addc_u32 s55, s9, 0
	s_mul_i32 s8, s14, 0xc00
	s_mov_b32 s9, s13
	s_lshl_b64 s[8:9], s[8:9], 2
	v_readlane_b32 s3, v254, 49
	s_add_u32 s8, s3, s8
	v_readlane_b32 s3, v254, 50
	v_readlane_b32 s62, v252, 24
	s_addc_u32 s9, s3, s9
	v_readlane_b32 s63, v252, 25
	s_add_u32 s62, s8, 0x2000
	s_addc_u32 s63, s9, 0
	s_add_i32 m0, s97, 0x18000
	v_lshl_add_u64 v[0:1], v[0:1], 0, s[68:69]
	global_load_lds_dwordx4 v[0:1], off
	v_lshl_add_u64 v[0:1], v[2:3], 0, s[68:69]
	s_add_i32 m0, s97, 0x1a000
	s_add_i32 s53, s97, 0x8000
	global_load_lds_dwordx4 v[0:1], off
	v_lshl_add_u64 v[0:1], v[8:9], 0, s[68:69]
	s_mov_b32 m0, s53
	s_add_i32 s56, s97, 0xa000
	global_load_lds_dwordx4 v[0:1], off
	v_lshl_add_u64 v[0:1], v[10:11], 0, s[68:69]
	s_mov_b32 m0, s56
	v_bfe_u32 v18, v229, 4, 2
	global_load_lds_dwordx4 v[0:1], off
	s_add_i32 m0, s97, 0x1c000
	v_lshl_add_u64 v[0:1], v[4:5], 0, s[68:69]
	global_load_lds_dwordx4 v[0:1], off
	v_lshl_add_u64 v[0:1], v[6:7], 0, s[68:69]
	s_add_i32 m0, s97, 0x1e000
	v_and_b32_e32 v19, 15, v229
	global_load_lds_dwordx4 v[0:1], off
	v_lshlrev_b32_e32 v21, 4, v18
	v_readlane_b32 s52, v252, 14
	v_lshl_or_b32 v231, s6, 6, v19
	v_lshl_or_b32 v19, v19, 6, v21
	v_lshlrev_b32_e32 v21, 2, v229
	s_and_b32 s7, s7, 3
	s_lshr_b32 s52, s5, 6
	s_lshl_b32 s5, s6, 13
	v_and_b32_e32 v22, 32, v21
	v_bitop3_b32 v23, v19, s5, v22 bitop3:0xde
	s_lshl_b32 s5, s7, 12
	s_add_i32 s57, s52, -2
	s_movk_i32 s3, 0x100
	s_cmpk_lt_u32 s4, 0x100
	v_cmp_gt_i32_e64 s[10:11], s3, v229
	s_cselect_b64 s[64:65], -1, 0
	v_readlane_b32 s3, v254, 45
	s_lshl_b32 s6, s7, 7
	s_add_i32 s8, s3, s6
	s_add_i32 s6, s6, 0
	v_lshlrev_b32_e32 v0, 5, v18
	s_add_i32 s6, s6, 0x21400
	v_and_b32_e32 v1, 64, v228
	v_add_u32_e32 v234, s8, v0
	v_add_u32_e32 v235, s6, v0
	v_xor_b32_e32 v0, 16, v228
	v_add_u32_e32 v1, 64, v1
	v_cmp_lt_i32_e32 vcc, v0, v1
	s_lshl_b32 s6, s7, 2
	s_waitcnt vmcnt(8)
	s_barrier
	s_waitcnt vmcnt(6)
	s_add_i32 s6, s6, 0
	v_cndmask_b32_e32 v0, v228, v0, vcc
	v_lshlrev_b32_e32 v236, 2, v0
	v_xor_b32_e32 v0, 32, v228
	v_cmp_lt_i32_e32 vcc, v0, v1
	v_mov_b32_e32 v1, v193
	v_readlane_b32 s60, v252, 22
	v_cndmask_b32_e32 v0, v228, v0, vcc
	v_lshlrev_b32_e32 v237, 2, v0
	v_add_u32_e32 v0, v17, v15
	v_add_lshl_u32 v0, v0, v16, 1
	v_lshl_add_u64 v[204:205], s[12:13], 0, v[0:1]
	v_add_u32_e32 v0, v14, v12
	v_lshlrev_b32_e32 v20, 3, v18
	v_add_u32_e32 v233, s3, v21
	s_add_i32 s6, s6, 0x20000
	v_add_lshl_u32 v0, v0, v13, 1
	v_readlane_b32 s3, v254, 17
	s_mov_b32 s79, 0
	v_readlane_b32 s58, v252, 20
	v_readlane_b32 s59, v252, 21
	v_bitop3_b32 v232, s5, v19, v22 bitop3:0xf6
	v_cmp_eq_u32_e64 s[4:5], 0, v18
	v_lshl_add_u32 v238, v231, 4, s6
	v_lshl_or_b32 v239, s7, 5, v20
	v_lshl_add_u64 v[206:207], s[12:13], 0, v[0:1]
	v_add_u32_e32 v240, 0, v23
	v_readlane_b32 s60, v254, 16
	s_mov_b32 s66, s3
	v_readlane_b32 s61, v252, 23
	s_barrier
	s_branch .LBB0_552
